# peeled first K-loop iteration: its first super-phase no longer carries a vmcnt wait (K-tile 0 is complete before the loop; the in-order wait only drained the previous epilogue's stores and atomics)
# baseline (speedup 1.0000x reference)
; #define PG8_STAGE(bufoff, gbase, voff) do { _Pragma("unroll") for (int _i = 0; _i < 2; ++_i) \
;         __builtin_amdgcn_global_load_lds((const unsigned*)((const char*)(gbase) + (voff)[_i]), (PG8_LAS unsigned*)(lds + (bufoff) + ldsw + _i * 8192), 16, 0, 0); } while (0)
; #define PG8_LDA(dst, b, h) do { _Pragma("unroll") for (int m = 0; m < 4; ++m) _Pragma("unroll") for (int k = 0; k < 2; ++k) dst[m][k] = *(const PG8_LAS bf16x8*)(lds + PG8_SA(b, h) + aoff + m * 2048 + k * 1024); } while (0)
; #define PG8_LDB(dst, b, h) do { _Pragma("unroll") for (int n = 0; n < 2; ++n) _Pragma("unroll") for (int k = 0; k < 2; ++k) dst[n][k] = *(const PG8_LAS bf16x8*)(lds + PG8_SB(b, h) + boff + n * 2048 + k * 1024); } while (0)
; #define PG8_WAIT_V(n) asm volatile("s_waitcnt vmcnt(" #n ")" ::: "memory")
; #define PG8_WAIT_L(n) asm volatile("s_waitcnt lgkmcnt(" #n ")" ::: "memory")
; #define PG8_BAR __builtin_amdgcn_s_barrier()
; #define PG8_SCHED __builtin_amdgcn_sched_barrier(0)
; template <class Epi, class Sched, bool ALIGN_EPI = false, bool SP2 = false>
; __device__ __forceinline__ void gemm_phase(PG8_LAS unsigned char* lds, const Gemm g, const Sched& S, const Epi& E) {
;     ...
;         const bool has_next = S.next(ui + 1, nxt);
;         const char* nA = has_next ? (const char*)g.A + (size_t)nxt.pm * tstep : cA; const char* nB = has_next ? (const char*)g.Bt + (size_t)nxt.pn * tstep : cB;
;         for (int t = 0; t < nt; t += 2) {
;             const bool last = (t == nt - 2);
;             const char* a1 = cA + (size_t)(t + 1) * kstep;
;             const char* a2 = last ? nA : cA + (size_t)(t + 2) * kstep; const char* b2 = last ? nB : cB + (size_t)(t + 2) * kstep;
;             const char* a3 = a2 + kstep; const char* b3 = b2 + kstep;
;             if (last && has_next) S.a_ready(nxt);
;             if constexpr (SP2) {
;             PG8_LDB(B0, 0, 0); PG8_LDB(B1, 0, 1); PG8_SCHED; PG8_LDA(At, 0, 0); PG8_STAGE(PG8_SA(1, 1), a1 + hstep, voffA);
;             PG8_WAIT_V(8); PG8_WAIT_L(0); PG8_BAR; PG8_MMA(0, 0, At, B0); PG8_MMA(0, 1, At, B1); PG8_BAR; PG8_SCHED;
;             PG8_LDA(At, 0, 1); PG8_STAGE(PG8_SB(0, 0), b2, voffB); PG8_STAGE(PG8_SB(0, 1), b2 + hstep, voffB); PG8_STAGE(PG8_SA(0, 0), a2, voffA);
;             PG8_WAIT_V(8); PG8_WAIT_L(0); PG8_BAR; PG8_MMA(1, 0, At, B0); PG8_MMA(1, 1, At, B1); PG8_BAR; PG8_SCHED;
.Lstg_done:
	s_ashr_i32 s27, s26, 31
	s_lshl_b64 s[12:13], s[26:27], 20
	s_add_u32 s94, s18, s12
	s_addc_u32 s95, s19, s13
	s_and_b64 s[12:13], s[46:47], exec
	s_cselect_b32 s27, s95, s69
	s_cselect_b32 s86, s94, s68
	s_ashr_i32 s17, s16, 31
	s_lshl_b64 s[12:13], s[16:17], 20
	v_readlane_b32 s14, v254, 38
	v_readlane_b32 s15, v254, 39
	s_add_u32 s14, s14, s12
	s_addc_u32 s15, s15, s13
	s_and_b64 s[12:13], s[46:47], exec
	s_cselect_b32 s17, s15, s11
	s_cselect_b32 s88, s14, s10
	s_add_u32 vcc_lo, s68, 0x80080
	s_addc_u32 vcc_hi, s69, 0
	s_add_u32 s21, s10, 0x100
	s_addc_u32 s12, s11, 0
	s_mov_b32 s13, -2
	v_add_u32_e32 v218, 0x10000, v194
	s_add_u32 s10, vcc_lo, 0xfff80080
	s_addc_u32 s11, vcc_hi, -1
	s_add_i32 s84, 0, 0x10000
	s_cmp_eq_u32 s13, 28
	s_cselect_b32 s69, s27, s11
	s_cselect_b32 s68, s86, s10
	s_cselect_b32 s11, s17, s12
	s_cselect_b32 s10, s88, s21
	s_add_i32 s93, 0, 0x14000
	ds_read_b128 v[114:117], v218
	ds_read_b128 v[118:121], v218 offset:1024
	ds_read_b128 v[130:133], v218 offset:2048
	ds_read_b128 v[138:141], v218 offset:3072
	ds_read_b128 v[146:149], v218 offset:16384
	ds_read_b128 v[156:159], v218 offset:17408
	ds_read_b128 v[160:163], v218 offset:18432
	ds_read_b128 v[164:167], v218 offset:19456
	s_add_i32 m0, s2, 0xc000
	ds_read_b128 v[168:171], v199
	ds_read_b128 v[172:175], v199 offset:1024
	ds_read_b128 v[176:179], v199 offset:2048
	ds_read_b128 v[180:183], v199 offset:3072
	ds_read_b128 v[184:187], v199 offset:4096
	ds_read_b128 v[188:191], v199 offset:5120
	ds_read_b128 v[200:203], v199 offset:6144
	ds_read_b128 v[204:207], v199 offset:7168
	global_load_lds_dwordx4 v152, vcc
	s_add_i32 m0, s2, 0xe000
	s_nop 0
	global_load_lds_dwordx4 v154, vcc
	s_waitcnt lgkmcnt(0)
	s_setprio 1
	s_barrier
	v_mfma_f32_16x16x32_bf16 v[142:145], v[114:117], v[168:171], 0
	v_mfma_f32_16x16x32_bf16 v[62:65], v[130:133], v[168:171], 0
	v_mfma_f32_16x16x32_bf16 v[122:125], v[114:117], v[176:179], 0
	v_mfma_f32_16x16x32_bf16 v[50:53], v[130:133], v[176:179], 0
	v_mfma_f32_16x16x32_bf16 v[106:109], v[114:117], v[184:187], 0
	v_mfma_f32_16x16x32_bf16 v[42:45], v[130:133], v[184:187], 0
	v_mfma_f32_16x16x32_bf16 v[98:101], v[114:117], v[200:203], 0
	v_mfma_f32_16x16x32_bf16 v[34:37], v[130:133], v[200:203], 0
	v_mfma_f32_16x16x32_bf16 v[142:145], v[118:121], v[172:175], v[142:145]
	v_mfma_f32_16x16x32_bf16 v[62:65], v[138:141], v[172:175], v[62:65]
	v_mfma_f32_16x16x32_bf16 v[122:125], v[118:121], v[180:183], v[122:125]
	v_mfma_f32_16x16x32_bf16 v[50:53], v[138:141], v[180:183], v[50:53]
	v_mfma_f32_16x16x32_bf16 v[106:109], v[118:121], v[188:191], v[106:109]
	v_mfma_f32_16x16x32_bf16 v[42:45], v[138:141], v[188:191], v[42:45]
	v_mfma_f32_16x16x32_bf16 v[98:101], v[118:121], v[204:207], v[98:101]
	v_mfma_f32_16x16x32_bf16 v[34:37], v[138:141], v[204:207], v[34:37]
	v_mfma_f32_16x16x32_bf16 v[134:137], v[146:149], v[168:171], 0
	v_mfma_f32_16x16x32_bf16 v[58:61], v[160:163], v[168:171], 0
	v_mfma_f32_16x16x32_bf16 v[126:129], v[146:149], v[176:179], 0
	v_mfma_f32_16x16x32_bf16 v[54:57], v[160:163], v[176:179], 0
	v_mfma_f32_16x16x32_bf16 v[110:113], v[146:149], v[184:187], 0
	v_mfma_f32_16x16x32_bf16 v[46:49], v[160:163], v[184:187], 0
	v_mfma_f32_16x16x32_bf16 v[102:105], v[146:149], v[200:203], 0
	v_mfma_f32_16x16x32_bf16 v[38:41], v[160:163], v[200:203], 0
	v_mfma_f32_16x16x32_bf16 v[134:137], v[156:159], v[172:175], v[134:137]
	v_mfma_f32_16x16x32_bf16 v[58:61], v[164:167], v[172:175], v[58:61]
	v_mfma_f32_16x16x32_bf16 v[126:129], v[156:159], v[180:183], v[126:129]
	v_mfma_f32_16x16x32_bf16 v[54:57], v[164:167], v[180:183], v[54:57]
	v_mfma_f32_16x16x32_bf16 v[110:113], v[156:159], v[188:191], v[110:113]
	v_mfma_f32_16x16x32_bf16 v[46:49], v[164:167], v[188:191], v[46:49]
	v_mfma_f32_16x16x32_bf16 v[102:105], v[156:159], v[204:207], v[102:105]
	v_mfma_f32_16x16x32_bf16 v[38:41], v[164:167], v[204:207], v[38:41]
	s_barrier
	s_setprio 0
	s_add_i32 s84, s84, s1
	s_add_u32 s100, s10, 0x80
	s_addc_u32 s101, s11, 0
	s_mov_b32 m0, s84
	ds_read_b128 v[168:171], v199 offset:16384
	ds_read_b128 v[172:175], v199 offset:17408
	ds_read_b128 v[176:179], v199 offset:18432
	ds_read_b128 v[180:183], v199 offset:19456
	ds_read_b128 v[184:187], v199 offset:20480
	ds_read_b128 v[188:191], v199 offset:21504
	ds_read_b128 v[200:203], v199 offset:22528
	ds_read_b128 v[204:207], v199 offset:23552
	global_load_lds_dwordx4 v0, s[10:11]
	s_add_i32 m0, s84, 0x2000
	s_add_u32 s84, s10, 0x80000
	s_addc_u32 s85, s11, 0
	s_add_i32 s93, s93, s1
	global_load_lds_dwordx4 v150, s[10:11]
	s_mov_b32 m0, s93
	s_add_u32 s98, s68, 0x80
	s_addc_u32 s99, s69, 0
	global_load_lds_dwordx4 v0, s[84:85]
	s_add_i32 m0, s93, 0x2000
	s_nop 0
	global_load_lds_dwordx4 v150, s[84:85]
	s_mov_b32 m0, s2
	s_nop 0
	global_load_lds_dwordx4 v0, s[68:69]
	s_mov_b32 m0, s4
	s_nop 0
	global_load_lds_dwordx4 v150, s[68:69]
	s_waitcnt vmcnt(8) lgkmcnt(0)
	s_setprio 1
	s_barrier
; #define PG8_STAGE(bufoff, gbase, voff) do { _Pragma("unroll") for (int _i = 0; _i < 2; ++_i) \
;         __builtin_amdgcn_global_load_lds((const unsigned*)((const char*)(gbase) + (voff)[_i]), (PG8_LAS unsigned*)(lds + (bufoff) + ldsw + _i * 8192), 16, 0, 0); } while (0)
; #define PG8_LDA(dst, b, h) do { _Pragma("unroll") for (int m = 0; m < 4; ++m) _Pragma("unroll") for (int k = 0; k < 2; ++k) dst[m][k] = *(const PG8_LAS bf16x8*)(lds + PG8_SA(b, h) + aoff + m * 2048 + k * 1024); } while (0)
; #define PG8_LDB(dst, b, h) do { _Pragma("unroll") for (int n = 0; n < 2; ++n) _Pragma("unroll") for (int k = 0; k < 2; ++k) dst[n][k] = *(const PG8_LAS bf16x8*)(lds + PG8_SB(b, h) + boff + n * 2048 + k * 1024); } while (0)
; #define PG8_MMA(ai, bj, At, Bt) do { __builtin_amdgcn_s_setprio(1); _Pragma("unroll") for (int m = 0; m < 4; ++m) _Pragma("unroll") for (int n = 0; n < 2; ++n) _Pragma("unroll") for (int k = 0; k < 2; ++k) \
;         acc[ai][bj][m][n] = __builtin_amdgcn_mfma_f32_16x16x32_bf16(Bt[n][k], At[m][k], acc[ai][bj][m][n], 0, 0, 0); __builtin_amdgcn_s_setprio(0); } while (0)
; #define PG8_WAIT_V(n) asm volatile("s_waitcnt vmcnt(" #n ")" ::: "memory")
; #define PG8_WAIT_L(n) asm volatile("s_waitcnt lgkmcnt(" #n ")" ::: "memory")
; #define PG8_BAR __builtin_amdgcn_s_barrier()
; #define PG8_SCHED __builtin_amdgcn_sched_barrier(0)
; template <class Epi, class Sched, bool ALIGN_EPI = false, bool SP2 = false>
; __device__ __forceinline__ void gemm_phase(PG8_LAS unsigned char* lds, const Gemm g, const Sched& S, const Epi& E) {
;     ...
;             PG8_LDA(At, 0, 1); PG8_STAGE(PG8_SB(0, 0), b2, voffB); PG8_STAGE(PG8_SB(0, 1), b2 + hstep, voffB); PG8_STAGE(PG8_SA(0, 0), a2, voffA);
;             PG8_WAIT_V(8); PG8_WAIT_L(0); PG8_BAR; PG8_MMA(1, 0, At, B0); PG8_MMA(1, 1, At, B1); PG8_BAR; PG8_SCHED;
;             PG8_LDB(B0, 1, 0); PG8_LDB(B1, 1, 1); PG8_SCHED; PG8_LDA(At, 1, 0); PG8_STAGE(PG8_SA(0, 1), a2 + hstep, voffA);
;             PG8_WAIT_V(8); PG8_WAIT_L(0); PG8_BAR; PG8_MMA(0, 0, At, B0); PG8_MMA(0, 1, At, B1); PG8_BAR; PG8_SCHED;
	v_mfma_f32_16x16x32_bf16 v[94:97], v[114:117], v[168:171], 0
	v_mfma_f32_16x16x32_bf16 v[30:33], v[130:133], v[168:171], 0
	v_mfma_f32_16x16x32_bf16 v[82:85], v[114:117], v[176:179], 0
	v_mfma_f32_16x16x32_bf16 v[18:21], v[130:133], v[176:179], 0
	v_mfma_f32_16x16x32_bf16 v[74:77], v[114:117], v[184:187], 0
	v_mfma_f32_16x16x32_bf16 v[10:13], v[130:133], v[184:187], 0
	v_mfma_f32_16x16x32_bf16 v[66:69], v[114:117], v[200:203], 0
	v_mfma_f32_16x16x32_bf16 v[2:5], v[130:133], v[200:203], 0
	v_mfma_f32_16x16x32_bf16 v[94:97], v[118:121], v[172:175], v[94:97]
	v_mfma_f32_16x16x32_bf16 v[30:33], v[138:141], v[172:175], v[30:33]
	v_mfma_f32_16x16x32_bf16 v[82:85], v[118:121], v[180:183], v[82:85]
	v_mfma_f32_16x16x32_bf16 v[18:21], v[138:141], v[180:183], v[18:21]
	v_mfma_f32_16x16x32_bf16 v[74:77], v[118:121], v[188:191], v[74:77]
	v_mfma_f32_16x16x32_bf16 v[10:13], v[138:141], v[188:191], v[10:13]
	v_mfma_f32_16x16x32_bf16 v[66:69], v[118:121], v[204:207], v[66:69]
	v_mfma_f32_16x16x32_bf16 v[2:5], v[138:141], v[204:207], v[2:5]
	v_mfma_f32_16x16x32_bf16 v[90:93], v[146:149], v[168:171], 0
	v_mfma_f32_16x16x32_bf16 v[26:29], v[160:163], v[168:171], 0
	v_mfma_f32_16x16x32_bf16 v[86:89], v[146:149], v[176:179], 0
	v_mfma_f32_16x16x32_bf16 v[22:25], v[160:163], v[176:179], 0
	v_mfma_f32_16x16x32_bf16 v[78:81], v[146:149], v[184:187], 0
	v_mfma_f32_16x16x32_bf16 v[14:17], v[160:163], v[184:187], 0
	v_mfma_f32_16x16x32_bf16 v[70:73], v[146:149], v[200:203], 0
	v_mfma_f32_16x16x32_bf16 v[6:9], v[160:163], v[200:203], 0
	v_mfma_f32_16x16x32_bf16 v[90:93], v[156:159], v[172:175], v[90:93]
	v_mfma_f32_16x16x32_bf16 v[26:29], v[164:167], v[172:175], v[26:29]
	v_mfma_f32_16x16x32_bf16 v[86:89], v[156:159], v[180:183], v[86:89]
	v_mfma_f32_16x16x32_bf16 v[22:25], v[164:167], v[180:183], v[22:25]
	v_mfma_f32_16x16x32_bf16 v[78:81], v[156:159], v[188:191], v[78:81]
	v_mfma_f32_16x16x32_bf16 v[14:17], v[164:167], v[188:191], v[14:17]
	v_mfma_f32_16x16x32_bf16 v[70:73], v[156:159], v[204:207], v[70:73]
	v_mfma_f32_16x16x32_bf16 v[6:9], v[164:167], v[204:207], v[6:9]
	s_barrier
	s_setprio 0
	s_add_i32 s84, 0, 0x18000
	s_add_i32 s85, 0, 0x1c000
	ds_read_b128 v[114:117], v218 offset:32768
	ds_read_b128 v[118:121], v218 offset:33792
	ds_read_b128 v[130:133], v218 offset:34816
	ds_read_b128 v[138:141], v218 offset:35840
	ds_read_b128 v[146:149], v218 offset:49152
	ds_read_b128 v[156:159], v218 offset:50176
	ds_read_b128 v[160:163], v218 offset:51200
	ds_read_b128 v[164:167], v218 offset:52224
	s_add_u32 s68, s68, 0x80000
	s_addc_u32 s69, s69, 0
	s_mov_b32 m0, s5
	ds_read_b128 v[168:171], v199 offset:32768
	ds_read_b128 v[172:175], v199 offset:33792
	ds_read_b128 v[176:179], v199 offset:34816
	ds_read_b128 v[180:183], v199 offset:35840
	ds_read_b128 v[184:187], v199 offset:36864
	ds_read_b128 v[188:191], v199 offset:37888
	ds_read_b128 v[200:203], v199 offset:38912
	ds_read_b128 v[204:207], v199 offset:39936
	global_load_lds_dwordx4 v0, s[68:69]
	s_mov_b32 m0, s6
	s_nop 0
	global_load_lds_dwordx4 v150, s[68:69]
	s_waitcnt vmcnt(8) lgkmcnt(0)
	s_setprio 1
	s_barrier
	v_mfma_f32_16x16x32_bf16 v[142:145], v[114:117], v[168:171], v[142:145]
	v_mfma_f32_16x16x32_bf16 v[62:65], v[130:133], v[168:171], v[62:65]
	v_mfma_f32_16x16x32_bf16 v[122:125], v[114:117], v[176:179], v[122:125]
	v_mfma_f32_16x16x32_bf16 v[50:53], v[130:133], v[176:179], v[50:53]
	v_mfma_f32_16x16x32_bf16 v[106:109], v[114:117], v[184:187], v[106:109]
	v_mfma_f32_16x16x32_bf16 v[42:45], v[130:133], v[184:187], v[42:45]
	v_mfma_f32_16x16x32_bf16 v[98:101], v[114:117], v[200:203], v[98:101]
	v_mfma_f32_16x16x32_bf16 v[34:37], v[130:133], v[200:203], v[34:37]
	v_mfma_f32_16x16x32_bf16 v[142:145], v[118:121], v[172:175], v[142:145]
	v_mfma_f32_16x16x32_bf16 v[62:65], v[138:141], v[172:175], v[62:65]
	v_mfma_f32_16x16x32_bf16 v[122:125], v[118:121], v[180:183], v[122:125]
	v_mfma_f32_16x16x32_bf16 v[50:53], v[138:141], v[180:183], v[50:53]
	v_mfma_f32_16x16x32_bf16 v[106:109], v[118:121], v[188:191], v[106:109]
	v_mfma_f32_16x16x32_bf16 v[42:45], v[138:141], v[188:191], v[42:45]
	v_mfma_f32_16x16x32_bf16 v[98:101], v[118:121], v[204:207], v[98:101]
	v_mfma_f32_16x16x32_bf16 v[34:37], v[138:141], v[204:207], v[34:37]
	v_mfma_f32_16x16x32_bf16 v[134:137], v[146:149], v[168:171], v[134:137]
	v_mfma_f32_16x16x32_bf16 v[58:61], v[160:163], v[168:171], v[58:61]
	v_mfma_f32_16x16x32_bf16 v[126:129], v[146:149], v[176:179], v[126:129]
	v_mfma_f32_16x16x32_bf16 v[54:57], v[160:163], v[176:179], v[54:57]
	v_mfma_f32_16x16x32_bf16 v[110:113], v[146:149], v[184:187], v[110:113]
	v_mfma_f32_16x16x32_bf16 v[46:49], v[160:163], v[184:187], v[46:49]
	v_mfma_f32_16x16x32_bf16 v[102:105], v[146:149], v[200:203], v[102:105]
	v_mfma_f32_16x16x32_bf16 v[38:41], v[160:163], v[200:203], v[38:41]
	v_mfma_f32_16x16x32_bf16 v[134:137], v[156:159], v[172:175], v[134:137]
	v_mfma_f32_16x16x32_bf16 v[58:61], v[164:167], v[172:175], v[58:61]
	v_mfma_f32_16x16x32_bf16 v[126:129], v[156:159], v[180:183], v[126:129]
	v_mfma_f32_16x16x32_bf16 v[54:57], v[164:167], v[180:183], v[54:57]
	v_mfma_f32_16x16x32_bf16 v[110:113], v[156:159], v[188:191], v[110:113]
	v_mfma_f32_16x16x32_bf16 v[46:49], v[164:167], v[188:191], v[46:49]
	v_mfma_f32_16x16x32_bf16 v[102:105], v[156:159], v[204:207], v[102:105]
	v_mfma_f32_16x16x32_bf16 v[38:41], v[164:167], v[204:207], v[38:41]
	s_barrier
; #define PG8_STAGE(bufoff, gbase, voff) do { _Pragma("unroll") for (int _i = 0; _i < 2; ++_i) \
;         __builtin_amdgcn_global_load_lds((const unsigned*)((const char*)(gbase) + (voff)[_i]), (PG8_LAS unsigned*)(lds + (bufoff) + ldsw + _i * 8192), 16, 0, 0); } while (0)
; #define PG8_LDA(dst, b, h) do { _Pragma("unroll") for (int m = 0; m < 4; ++m) _Pragma("unroll") for (int k = 0; k < 2; ++k) dst[m][k] = *(const PG8_LAS bf16x8*)(lds + PG8_SA(b, h) + aoff + m * 2048 + k * 1024); } while (0)
; #define PG8_LDB(dst, b, h) do { _Pragma("unroll") for (int n = 0; n < 2; ++n) _Pragma("unroll") for (int k = 0; k < 2; ++k) dst[n][k] = *(const PG8_LAS bf16x8*)(lds + PG8_SB(b, h) + boff + n * 2048 + k * 1024); } while (0)
; #define PG8_MMA(ai, bj, At, Bt) do { __builtin_amdgcn_s_setprio(1); _Pragma("unroll") for (int m = 0; m < 4; ++m) _Pragma("unroll") for (int n = 0; n < 2; ++n) _Pragma("unroll") for (int k = 0; k < 2; ++k) \
;         acc[ai][bj][m][n] = __builtin_amdgcn_mfma_f32_16x16x32_bf16(Bt[n][k], At[m][k], acc[ai][bj][m][n], 0, 0, 0); __builtin_amdgcn_s_setprio(0); } while (0)
; #define PG8_WAIT_V(n) asm volatile("s_waitcnt vmcnt(" #n ")" ::: "memory")
; #define PG8_WAIT_L(n) asm volatile("s_waitcnt lgkmcnt(" #n ")" ::: "memory")
; #define PG8_BAR __builtin_amdgcn_s_barrier()
; #define PG8_SCHED __builtin_amdgcn_sched_barrier(0)
; template <class Epi, class Sched, bool ALIGN_EPI = false, bool SP2 = false>
; __device__ __forceinline__ void gemm_phase(PG8_LAS unsigned char* lds, const Gemm g, const Sched& S, const Epi& E) {
;     ...
;             PG8_LDB(B0, 1, 0); PG8_LDB(B1, 1, 1); PG8_SCHED; PG8_LDA(At, 1, 0); PG8_STAGE(PG8_SA(0, 1), a2 + hstep, voffA);
;             PG8_WAIT_V(8); PG8_WAIT_L(0); PG8_BAR; PG8_MMA(0, 0, At, B0); PG8_MMA(0, 1, At, B1); PG8_BAR; PG8_SCHED;
;             PG8_LDA(At, 1, 1); PG8_STAGE(PG8_SB(1, 0), b3, voffB); PG8_STAGE(PG8_SB(1, 1), b3 + hstep, voffB); PG8_STAGE(PG8_SA(1, 0), a3, voffA);
;             PG8_WAIT_V(8); PG8_WAIT_L(0); PG8_BAR; PG8_MMA(1, 0, At, B0); PG8_MMA(1, 1, At, B1); PG8_BAR; PG8_SCHED;
	s_setprio 0
	s_add_i32 s68, s84, s1
	s_mov_b32 m0, s68
	ds_read_b128 v[168:171], v199 offset:49152
	ds_read_b128 v[172:175], v199 offset:50176
	ds_read_b128 v[176:179], v199 offset:51200
	ds_read_b128 v[180:183], v199 offset:52224
	ds_read_b128 v[184:187], v199 offset:53248
	ds_read_b128 v[188:191], v199 offset:54272
	ds_read_b128 v[200:203], v199 offset:55296
	ds_read_b128 v[204:207], v199 offset:56320
	global_load_lds_dwordx4 v0, s[100:101]
	s_add_i32 m0, s68, 0x2000
	s_add_i32 s68, s85, s1
	global_load_lds_dwordx4 v150, s[100:101]
	s_add_u32 s10, s10, 0x80080
	s_addc_u32 s11, s11, 0
	s_mov_b32 m0, s68
	s_nop 0
	global_load_lds_dwordx4 v0, s[10:11]
	s_add_i32 m0, s68, 0x2000
	s_nop 0
	global_load_lds_dwordx4 v150, s[10:11]
	s_mov_b32 m0, s7
	s_nop 0
	global_load_lds_dwordx4 v0, s[98:99]
	s_mov_b32 m0, s30
	s_nop 0
	global_load_lds_dwordx4 v150, s[98:99]
	s_waitcnt vmcnt(8) lgkmcnt(0)
	s_setprio 1
	s_barrier
	v_mfma_f32_16x16x32_bf16 v[94:97], v[114:117], v[168:171], v[94:97]
	v_mfma_f32_16x16x32_bf16 v[30:33], v[130:133], v[168:171], v[30:33]
	v_mfma_f32_16x16x32_bf16 v[82:85], v[114:117], v[176:179], v[82:85]
	v_mfma_f32_16x16x32_bf16 v[18:21], v[130:133], v[176:179], v[18:21]
	v_mfma_f32_16x16x32_bf16 v[74:77], v[114:117], v[184:187], v[74:77]
	v_mfma_f32_16x16x32_bf16 v[10:13], v[130:133], v[184:187], v[10:13]
	v_mfma_f32_16x16x32_bf16 v[66:69], v[114:117], v[200:203], v[66:69]
	v_mfma_f32_16x16x32_bf16 v[2:5], v[130:133], v[200:203], v[2:5]
	v_mfma_f32_16x16x32_bf16 v[94:97], v[118:121], v[172:175], v[94:97]
	v_mfma_f32_16x16x32_bf16 v[30:33], v[138:141], v[172:175], v[30:33]
	v_mfma_f32_16x16x32_bf16 v[82:85], v[118:121], v[180:183], v[82:85]
	v_mfma_f32_16x16x32_bf16 v[18:21], v[138:141], v[180:183], v[18:21]
	v_mfma_f32_16x16x32_bf16 v[74:77], v[118:121], v[188:191], v[74:77]
	v_mfma_f32_16x16x32_bf16 v[10:13], v[138:141], v[188:191], v[10:13]
	v_mfma_f32_16x16x32_bf16 v[66:69], v[118:121], v[204:207], v[66:69]
	v_mfma_f32_16x16x32_bf16 v[2:5], v[138:141], v[204:207], v[2:5]
	v_mfma_f32_16x16x32_bf16 v[90:93], v[146:149], v[168:171], v[90:93]
	v_mfma_f32_16x16x32_bf16 v[26:29], v[160:163], v[168:171], v[26:29]
	v_mfma_f32_16x16x32_bf16 v[86:89], v[146:149], v[176:179], v[86:89]
	v_mfma_f32_16x16x32_bf16 v[22:25], v[160:163], v[176:179], v[22:25]
	v_mfma_f32_16x16x32_bf16 v[78:81], v[146:149], v[184:187], v[78:81]
	v_mfma_f32_16x16x32_bf16 v[14:17], v[160:163], v[184:187], v[14:17]
	v_mfma_f32_16x16x32_bf16 v[70:73], v[146:149], v[200:203], v[70:73]
	v_mfma_f32_16x16x32_bf16 v[6:9], v[160:163], v[200:203], v[6:9]
	v_mfma_f32_16x16x32_bf16 v[90:93], v[156:159], v[172:175], v[90:93]
	v_mfma_f32_16x16x32_bf16 v[26:29], v[164:167], v[172:175], v[26:29]
	v_mfma_f32_16x16x32_bf16 v[86:89], v[156:159], v[180:183], v[86:89]
	v_mfma_f32_16x16x32_bf16 v[22:25], v[164:167], v[180:183], v[22:25]
	v_mfma_f32_16x16x32_bf16 v[78:81], v[156:159], v[188:191], v[78:81]
	v_mfma_f32_16x16x32_bf16 v[14:17], v[164:167], v[188:191], v[14:17]
	v_mfma_f32_16x16x32_bf16 v[70:73], v[156:159], v[204:207], v[70:73]
	v_mfma_f32_16x16x32_bf16 v[6:9], v[164:167], v[204:207], v[6:9]
	s_barrier
	s_setprio 0
	s_add_i32 s13, s13, 2
	s_add_u32 vcc_lo, vcc_lo, 0x100
	s_addc_u32 vcc_hi, vcc_hi, 0
	s_add_u32 s21, s21, 0x100
	s_addc_u32 s12, s12, 0

; #define PG8_STAGE(bufoff, gbase, voff) do { _Pragma("unroll") for (int _i = 0; _i < 2; ++_i) \
;         __builtin_amdgcn_global_load_lds((const unsigned*)((const char*)(gbase) + (voff)[_i]), (PG8_LAS unsigned*)(lds + (bufoff) + ldsw + _i * 8192), 16, 0, 0); } while (0)
; #define PG8_LDA(dst, b, h) do { _Pragma("unroll") for (int m = 0; m < 4; ++m) _Pragma("unroll") for (int k = 0; k < 2; ++k) dst[m][k] = *(const PG8_LAS bf16x8*)(lds + PG8_SA(b, h) + aoff + m * 2048 + k * 1024); } while (0)
; #define PG8_LDB(dst, b, h) do { _Pragma("unroll") for (int n = 0; n < 2; ++n) _Pragma("unroll") for (int k = 0; k < 2; ++k) dst[n][k] = *(const PG8_LAS bf16x8*)(lds + PG8_SB(b, h) + boff + n * 2048 + k * 1024); } while (0)
; #define PG8_WAIT_V(n) asm volatile("s_waitcnt vmcnt(" #n ")" ::: "memory")
; #define PG8_WAIT_L(n) asm volatile("s_waitcnt lgkmcnt(" #n ")" ::: "memory")
; #define PG8_BAR __builtin_amdgcn_s_barrier()
; #define PG8_SCHED __builtin_amdgcn_sched_barrier(0)
; template <class Epi, class Sched, bool ALIGN_EPI = false, bool SP2 = false>
; __device__ __forceinline__ void gemm_phase(PG8_LAS unsigned char* lds, const Gemm g, const Sched& S, const Epi& E) {
;     ...
;         const char* nA = has_next ? (const char*)g.A + (size_t)nxt.pm * tstep : cA; const char* nB = has_next ? (const char*)g.Bt + (size_t)nxt.pn * tstep : cB;
;         for (int t = 0; t < nt; t += 2) {
;             const bool last = (t == nt - 2);
;             const char* a1 = cA + (size_t)(t + 1) * kstep;
;             const char* a2 = last ? nA : cA + (size_t)(t + 2) * kstep; const char* b2 = last ? nB : cB + (size_t)(t + 2) * kstep;
;             const char* a3 = a2 + kstep; const char* b3 = b2 + kstep;
;             if (last && has_next) S.a_ready(nxt);
;             if constexpr (SP2) {
;             PG8_LDB(B0, 0, 0); PG8_LDB(B1, 0, 1); PG8_SCHED; PG8_LDA(At, 0, 0); PG8_STAGE(PG8_SA(1, 1), a1 + hstep, voffA);
;             PG8_WAIT_V(8); PG8_WAIT_L(0); PG8_BAR; PG8_MMA(0, 0, At, B0); PG8_MMA(0, 1, At, B1); PG8_BAR; PG8_SCHED;
;             PG8_LDA(At, 0, 1); PG8_STAGE(PG8_SB(0, 0), b2, voffB); PG8_STAGE(PG8_SB(0, 1), b2 + hstep, voffB); PG8_STAGE(PG8_SA(0, 0), a2, voffA);
;             PG8_WAIT_V(8); PG8_WAIT_L(0); PG8_BAR; PG8_MMA(1, 0, At, B0); PG8_MMA(1, 1, At, B1); PG8_BAR; PG8_SCHED;
.LBB0_222:
	s_add_u32 s8, s8, 0x80
	s_addc_u32 s9, s9, 0
	s_add_u32 s12, s10, 0x100
	s_addc_u32 s13, s11, 0
	s_mov_b32 s10, 0
	s_waitcnt lgkmcnt(0)
	v_add_u32_e32 v218, 0x10000, v145
	s_add_i32 s14, s10, 2
	s_add_u32 s15, s8, 0x80
	s_addc_u32 s11, s9, 0
	s_add_i32 s64, 0, 0x10000
	s_cmp_eq_u32 s57, s10
	s_cselect_b32 s11, s51, s11
	s_cselect_b32 s10, s50, s15
	s_cselect_b32 s45, s53, s13
	s_cselect_b32 s44, s52, s12
	s_add_i32 s15, 0, 0x14000
	ds_read_b128 v[140:143], v218
	ds_read_b128 v[148:151], v218 offset:1024
	ds_read_b128 v[152:155], v218 offset:2048
	ds_read_b128 v[156:159], v218 offset:3072
	ds_read_b128 v[160:163], v218 offset:16384
	ds_read_b128 v[164:167], v218 offset:17408
	ds_read_b128 v[168:171], v218 offset:18432
	ds_read_b128 v[172:175], v218 offset:19456
	s_add_i32 m0, s21, 0xc000
	ds_read_b128 v[176:179], v147
	ds_read_b128 v[180:183], v147 offset:1024
	ds_read_b128 v[184:187], v147 offset:2048
	ds_read_b128 v[188:191], v147 offset:3072
	ds_read_b128 v[192:195], v147 offset:4096
	ds_read_b128 v[196:199], v147 offset:5120
	ds_read_b128 v[200:203], v147 offset:6144
	ds_read_b128 v[204:207], v147 offset:7168
	global_load_lds_dwordx4 v136, s[8:9]
	s_add_i32 m0, s21, 0xe000
	s_nop 0
	global_load_lds_dwordx4 v138, s[8:9]
	s_waitcnt lgkmcnt(0)
	s_setprio 1
	s_barrier
	v_mfma_f32_16x16x32_bf16 v[126:129], v[140:143], v[176:179], 0
	v_mfma_f32_16x16x32_bf16 v[122:125], v[152:155], v[176:179], 0
	v_mfma_f32_16x16x32_bf16 v[110:113], v[140:143], v[184:187], 0
	v_mfma_f32_16x16x32_bf16 v[106:109], v[152:155], v[184:187], 0
	v_mfma_f32_16x16x32_bf16 v[94:97], v[140:143], v[192:195], 0
	v_mfma_f32_16x16x32_bf16 v[90:93], v[152:155], v[192:195], 0
	v_mfma_f32_16x16x32_bf16 v[78:81], v[140:143], v[200:203], 0
	v_mfma_f32_16x16x32_bf16 v[74:77], v[152:155], v[200:203], 0
	v_mfma_f32_16x16x32_bf16 v[126:129], v[148:151], v[180:183], v[126:129]
	v_mfma_f32_16x16x32_bf16 v[122:125], v[156:159], v[180:183], v[122:125]
	v_mfma_f32_16x16x32_bf16 v[110:113], v[148:151], v[188:191], v[110:113]
	v_mfma_f32_16x16x32_bf16 v[106:109], v[156:159], v[188:191], v[106:109]
	v_mfma_f32_16x16x32_bf16 v[94:97], v[148:151], v[196:199], v[94:97]
	v_mfma_f32_16x16x32_bf16 v[90:93], v[156:159], v[196:199], v[90:93]
	v_mfma_f32_16x16x32_bf16 v[78:81], v[148:151], v[204:207], v[78:81]
	v_mfma_f32_16x16x32_bf16 v[74:77], v[156:159], v[204:207], v[74:77]
	v_mfma_f32_16x16x32_bf16 v[118:121], v[160:163], v[176:179], 0
	v_mfma_f32_16x16x32_bf16 v[114:117], v[168:171], v[176:179], 0
	v_mfma_f32_16x16x32_bf16 v[102:105], v[160:163], v[184:187], 0
	v_mfma_f32_16x16x32_bf16 v[98:101], v[168:171], v[184:187], 0
	v_mfma_f32_16x16x32_bf16 v[86:89], v[160:163], v[192:195], 0
	v_mfma_f32_16x16x32_bf16 v[82:85], v[168:171], v[192:195], 0
	v_mfma_f32_16x16x32_bf16 v[70:73], v[160:163], v[200:203], 0
	v_mfma_f32_16x16x32_bf16 v[66:69], v[168:171], v[200:203], 0
	v_mfma_f32_16x16x32_bf16 v[118:121], v[164:167], v[180:183], v[118:121]
	v_mfma_f32_16x16x32_bf16 v[114:117], v[172:175], v[180:183], v[114:117]
	v_mfma_f32_16x16x32_bf16 v[102:105], v[164:167], v[188:191], v[102:105]
	v_mfma_f32_16x16x32_bf16 v[98:101], v[172:175], v[188:191], v[98:101]
	v_mfma_f32_16x16x32_bf16 v[86:89], v[164:167], v[196:199], v[86:89]
	v_mfma_f32_16x16x32_bf16 v[82:85], v[172:175], v[196:199], v[82:85]
	v_mfma_f32_16x16x32_bf16 v[70:73], v[164:167], v[204:207], v[70:73]
	v_mfma_f32_16x16x32_bf16 v[66:69], v[172:175], v[204:207], v[66:69]
	s_barrier
	s_setprio 0
	s_add_i32 s64, s64, s7
	s_add_u32 s98, s44, 0x80
	s_addc_u32 s99, s45, 0
	s_mov_b32 m0, s64
	ds_read_b128 v[176:179], v147 offset:16384
	ds_read_b128 v[180:183], v147 offset:17408
	ds_read_b128 v[184:187], v147 offset:18432
	ds_read_b128 v[188:191], v147 offset:19456
	ds_read_b128 v[192:195], v147 offset:20480
	ds_read_b128 v[196:199], v147 offset:21504
	ds_read_b128 v[200:203], v147 offset:22528
	ds_read_b128 v[204:207], v147 offset:23552
	global_load_lds_dwordx4 v0, s[44:45]
	s_add_i32 m0, s64, 0x2000
	s_add_i32 s15, s15, s7
	global_load_lds_dwordx4 v134, s[44:45]
	s_add_u32 s44, s44, s30
	s_addc_u32 s45, s45, 0
	s_add_u32 s100, s44, 0x80
	s_addc_u32 s101, s45, 0
	s_mov_b32 m0, s15
	s_add_u32 vcc_lo, s10, 0x80
	s_addc_u32 vcc_hi, s11, 0
	global_load_lds_dwordx4 v0, s[44:45]
	s_add_i32 m0, s15, 0x2000
	s_nop 0
	global_load_lds_dwordx4 v134, s[44:45]
	s_mov_b32 m0, s21
	s_nop 0
	global_load_lds_dwordx4 v130, s[10:11]
	s_mov_b32 m0, s26
	s_nop 0
	global_load_lds_dwordx4 v132, s[10:11]
	s_waitcnt vmcnt(8) lgkmcnt(0)
	s_setprio 1
	s_barrier
	v_mfma_f32_16x16x32_bf16 v[62:65], v[140:143], v[176:179], 0
	v_mfma_f32_16x16x32_bf16 v[58:61], v[152:155], v[176:179], 0
	v_mfma_f32_16x16x32_bf16 v[46:49], v[140:143], v[184:187], 0
	v_mfma_f32_16x16x32_bf16 v[42:45], v[152:155], v[184:187], 0
	v_mfma_f32_16x16x32_bf16 v[30:33], v[140:143], v[192:195], 0
	v_mfma_f32_16x16x32_bf16 v[26:29], v[152:155], v[192:195], 0
	v_mfma_f32_16x16x32_bf16 v[14:17], v[140:143], v[200:203], 0
	v_mfma_f32_16x16x32_bf16 v[10:13], v[152:155], v[200:203], 0
	v_mfma_f32_16x16x32_bf16 v[62:65], v[148:151], v[180:183], v[62:65]
	v_mfma_f32_16x16x32_bf16 v[58:61], v[156:159], v[180:183], v[58:61]
	v_mfma_f32_16x16x32_bf16 v[46:49], v[148:151], v[188:191], v[46:49]
	v_mfma_f32_16x16x32_bf16 v[42:45], v[156:159], v[188:191], v[42:45]
	v_mfma_f32_16x16x32_bf16 v[30:33], v[148:151], v[196:199], v[30:33]
	v_mfma_f32_16x16x32_bf16 v[26:29], v[156:159], v[196:199], v[26:29]
	v_mfma_f32_16x16x32_bf16 v[14:17], v[148:151], v[204:207], v[14:17]
	v_mfma_f32_16x16x32_bf16 v[10:13], v[156:159], v[204:207], v[10:13]
	v_mfma_f32_16x16x32_bf16 v[54:57], v[160:163], v[176:179], 0
	v_mfma_f32_16x16x32_bf16 v[50:53], v[168:171], v[176:179], 0
	v_mfma_f32_16x16x32_bf16 v[38:41], v[160:163], v[184:187], 0
	v_mfma_f32_16x16x32_bf16 v[34:37], v[168:171], v[184:187], 0
	v_mfma_f32_16x16x32_bf16 v[22:25], v[160:163], v[192:195], 0
	v_mfma_f32_16x16x32_bf16 v[18:21], v[168:171], v[192:195], 0
	v_mfma_f32_16x16x32_bf16 v[6:9], v[160:163], v[200:203], 0
	v_mfma_f32_16x16x32_bf16 v[2:5], v[168:171], v[200:203], 0
	v_mfma_f32_16x16x32_bf16 v[54:57], v[164:167], v[180:183], v[54:57]
	v_mfma_f32_16x16x32_bf16 v[50:53], v[172:175], v[180:183], v[50:53]
	v_mfma_f32_16x16x32_bf16 v[38:41], v[164:167], v[188:191], v[38:41]
	v_mfma_f32_16x16x32_bf16 v[34:37], v[172:175], v[188:191], v[34:37]
	v_mfma_f32_16x16x32_bf16 v[22:25], v[164:167], v[196:199], v[22:25]
	v_mfma_f32_16x16x32_bf16 v[18:21], v[172:175], v[196:199], v[18:21]
	v_mfma_f32_16x16x32_bf16 v[6:9], v[164:167], v[204:207], v[6:9]
	v_mfma_f32_16x16x32_bf16 v[2:5], v[172:175], v[204:207], v[2:5]
	s_barrier
; #define PG8_STAGE(bufoff, gbase, voff) do { _Pragma("unroll") for (int _i = 0; _i < 2; ++_i) \
;         __builtin_amdgcn_global_load_lds((const unsigned*)((const char*)(gbase) + (voff)[_i]), (PG8_LAS unsigned*)(lds + (bufoff) + ldsw + _i * 8192), 16, 0, 0); } while (0)
; #define PG8_LDA(dst, b, h) do { _Pragma("unroll") for (int m = 0; m < 4; ++m) _Pragma("unroll") for (int k = 0; k < 2; ++k) dst[m][k] = *(const PG8_LAS bf16x8*)(lds + PG8_SA(b, h) + aoff + m * 2048 + k * 1024); } while (0)
; #define PG8_LDB(dst, b, h) do { _Pragma("unroll") for (int n = 0; n < 2; ++n) _Pragma("unroll") for (int k = 0; k < 2; ++k) dst[n][k] = *(const PG8_LAS bf16x8*)(lds + PG8_SB(b, h) + boff + n * 2048 + k * 1024); } while (0)
; #define PG8_MMA(ai, bj, At, Bt) do { __builtin_amdgcn_s_setprio(1); _Pragma("unroll") for (int m = 0; m < 4; ++m) _Pragma("unroll") for (int n = 0; n < 2; ++n) _Pragma("unroll") for (int k = 0; k < 2; ++k) \
;         acc[ai][bj][m][n] = __builtin_amdgcn_mfma_f32_16x16x32_bf16(Bt[n][k], At[m][k], acc[ai][bj][m][n], 0, 0, 0); __builtin_amdgcn_s_setprio(0); } while (0)
; #define PG8_WAIT_V(n) asm volatile("s_waitcnt vmcnt(" #n ")" ::: "memory")
; #define PG8_WAIT_L(n) asm volatile("s_waitcnt lgkmcnt(" #n ")" ::: "memory")
; #define PG8_BAR __builtin_amdgcn_s_barrier()
; #define PG8_SCHED __builtin_amdgcn_sched_barrier(0)
; template <class Epi, class Sched, bool ALIGN_EPI = false, bool SP2 = false>
; __device__ __forceinline__ void gemm_phase(PG8_LAS unsigned char* lds, const Gemm g, const Sched& S, const Epi& E) {
;     ...
;             PG8_LDB(B0, 1, 0); PG8_LDB(B1, 1, 1); PG8_SCHED; PG8_LDA(At, 1, 0); PG8_STAGE(PG8_SA(0, 1), a2 + hstep, voffA);
;             PG8_WAIT_V(8); PG8_WAIT_L(0); PG8_BAR; PG8_MMA(0, 0, At, B0); PG8_MMA(0, 1, At, B1); PG8_BAR; PG8_SCHED;
;             PG8_LDA(At, 1, 1); PG8_STAGE(PG8_SB(1, 0), b3, voffB); PG8_STAGE(PG8_SB(1, 1), b3 + hstep, voffB); PG8_STAGE(PG8_SA(1, 0), a3, voffA);
;             PG8_WAIT_V(8); PG8_WAIT_L(0); PG8_BAR; PG8_MMA(1, 0, At, B0); PG8_MMA(1, 1, At, B1); PG8_BAR; PG8_SCHED;
	s_setprio 0
	s_add_i32 s15, 0, 0x18000
	s_add_i32 s44, 0, 0x1c000
	ds_read_b128 v[140:143], v218 offset:32768
	ds_read_b128 v[148:151], v218 offset:33792
	ds_read_b128 v[152:155], v218 offset:34816
	ds_read_b128 v[156:159], v218 offset:35840
	ds_read_b128 v[160:163], v218 offset:49152
	ds_read_b128 v[164:167], v218 offset:50176
	ds_read_b128 v[168:171], v218 offset:51200
	ds_read_b128 v[172:175], v218 offset:52224
	s_add_u32 s10, s10, s30
	s_addc_u32 s11, s11, 0
	s_mov_b32 m0, s27
	ds_read_b128 v[176:179], v147 offset:32768
	ds_read_b128 v[180:183], v147 offset:33792
	ds_read_b128 v[184:187], v147 offset:34816
	ds_read_b128 v[188:191], v147 offset:35840
	ds_read_b128 v[192:195], v147 offset:36864
	ds_read_b128 v[196:199], v147 offset:37888
	ds_read_b128 v[200:203], v147 offset:38912
	ds_read_b128 v[204:207], v147 offset:39936
	global_load_lds_dwordx4 v130, s[10:11]
	s_mov_b32 m0, s54
	s_nop 0
	global_load_lds_dwordx4 v132, s[10:11]
	s_waitcnt vmcnt(8) lgkmcnt(0)
	s_setprio 1
	s_barrier
	v_mfma_f32_16x16x32_bf16 v[126:129], v[140:143], v[176:179], v[126:129]
	v_mfma_f32_16x16x32_bf16 v[122:125], v[152:155], v[176:179], v[122:125]
	v_mfma_f32_16x16x32_bf16 v[110:113], v[140:143], v[184:187], v[110:113]
	v_mfma_f32_16x16x32_bf16 v[106:109], v[152:155], v[184:187], v[106:109]
	v_mfma_f32_16x16x32_bf16 v[94:97], v[140:143], v[192:195], v[94:97]
	v_mfma_f32_16x16x32_bf16 v[90:93], v[152:155], v[192:195], v[90:93]
	v_mfma_f32_16x16x32_bf16 v[78:81], v[140:143], v[200:203], v[78:81]
	v_mfma_f32_16x16x32_bf16 v[74:77], v[152:155], v[200:203], v[74:77]
	v_mfma_f32_16x16x32_bf16 v[126:129], v[148:151], v[180:183], v[126:129]
	v_mfma_f32_16x16x32_bf16 v[122:125], v[156:159], v[180:183], v[122:125]
	v_mfma_f32_16x16x32_bf16 v[110:113], v[148:151], v[188:191], v[110:113]
	v_mfma_f32_16x16x32_bf16 v[106:109], v[156:159], v[188:191], v[106:109]
	v_mfma_f32_16x16x32_bf16 v[94:97], v[148:151], v[196:199], v[94:97]
	v_mfma_f32_16x16x32_bf16 v[90:93], v[156:159], v[196:199], v[90:93]
	v_mfma_f32_16x16x32_bf16 v[78:81], v[148:151], v[204:207], v[78:81]
	v_mfma_f32_16x16x32_bf16 v[74:77], v[156:159], v[204:207], v[74:77]
	v_mfma_f32_16x16x32_bf16 v[118:121], v[160:163], v[176:179], v[118:121]
	v_mfma_f32_16x16x32_bf16 v[114:117], v[168:171], v[176:179], v[114:117]
	v_mfma_f32_16x16x32_bf16 v[102:105], v[160:163], v[184:187], v[102:105]
	v_mfma_f32_16x16x32_bf16 v[98:101], v[168:171], v[184:187], v[98:101]
	v_mfma_f32_16x16x32_bf16 v[86:89], v[160:163], v[192:195], v[86:89]
	v_mfma_f32_16x16x32_bf16 v[82:85], v[168:171], v[192:195], v[82:85]
	v_mfma_f32_16x16x32_bf16 v[70:73], v[160:163], v[200:203], v[70:73]
	v_mfma_f32_16x16x32_bf16 v[66:69], v[168:171], v[200:203], v[66:69]
	v_mfma_f32_16x16x32_bf16 v[118:121], v[164:167], v[180:183], v[118:121]
	v_mfma_f32_16x16x32_bf16 v[114:117], v[172:175], v[180:183], v[114:117]
	v_mfma_f32_16x16x32_bf16 v[102:105], v[164:167], v[188:191], v[102:105]
	v_mfma_f32_16x16x32_bf16 v[98:101], v[172:175], v[188:191], v[98:101]
	v_mfma_f32_16x16x32_bf16 v[86:89], v[164:167], v[196:199], v[86:89]
	v_mfma_f32_16x16x32_bf16 v[82:85], v[172:175], v[196:199], v[82:85]
	v_mfma_f32_16x16x32_bf16 v[70:73], v[164:167], v[204:207], v[70:73]
	v_mfma_f32_16x16x32_bf16 v[66:69], v[172:175], v[204:207], v[66:69]
	s_barrier
	s_setprio 0
	s_add_i32 s10, s15, s7
	s_mov_b32 m0, s10
	ds_read_b128 v[176:179], v147 offset:49152
	ds_read_b128 v[180:183], v147 offset:50176
	ds_read_b128 v[184:187], v147 offset:51200
	ds_read_b128 v[188:191], v147 offset:52224
	ds_read_b128 v[192:195], v147 offset:53248
	ds_read_b128 v[196:199], v147 offset:54272
	ds_read_b128 v[200:203], v147 offset:55296
	ds_read_b128 v[204:207], v147 offset:56320
	global_load_lds_dwordx4 v0, s[98:99]
	s_add_i32 m0, s10, 0x2000
	s_add_i32 s10, s44, s7
	global_load_lds_dwordx4 v134, s[98:99]
	s_mov_b32 m0, s10
	s_nop 0
	global_load_lds_dwordx4 v0, s[100:101]
	s_add_i32 m0, s10, 0x2000
	s_nop 0
	global_load_lds_dwordx4 v134, s[100:101]
	s_mov_b32 m0, s16
	s_nop 0
	global_load_lds_dwordx4 v130, vcc
	s_mov_b32 m0, s17
	s_nop 0
	global_load_lds_dwordx4 v132, vcc
	s_waitcnt vmcnt(8) lgkmcnt(0)
	s_setprio 1
	s_barrier
	v_mfma_f32_16x16x32_bf16 v[62:65], v[140:143], v[176:179], v[62:65]
	v_mfma_f32_16x16x32_bf16 v[58:61], v[152:155], v[176:179], v[58:61]
	v_mfma_f32_16x16x32_bf16 v[46:49], v[140:143], v[184:187], v[46:49]
	v_mfma_f32_16x16x32_bf16 v[42:45], v[152:155], v[184:187], v[42:45]
	v_mfma_f32_16x16x32_bf16 v[30:33], v[140:143], v[192:195], v[30:33]
	v_mfma_f32_16x16x32_bf16 v[26:29], v[152:155], v[192:195], v[26:29]
	v_mfma_f32_16x16x32_bf16 v[14:17], v[140:143], v[200:203], v[14:17]
	v_mfma_f32_16x16x32_bf16 v[10:13], v[152:155], v[200:203], v[10:13]
	v_mfma_f32_16x16x32_bf16 v[62:65], v[148:151], v[180:183], v[62:65]
	v_mfma_f32_16x16x32_bf16 v[58:61], v[156:159], v[180:183], v[58:61]
	v_mfma_f32_16x16x32_bf16 v[46:49], v[148:151], v[188:191], v[46:49]
	v_mfma_f32_16x16x32_bf16 v[42:45], v[156:159], v[188:191], v[42:45]
	v_mfma_f32_16x16x32_bf16 v[30:33], v[148:151], v[196:199], v[30:33]
	v_mfma_f32_16x16x32_bf16 v[26:29], v[156:159], v[196:199], v[26:29]
	v_mfma_f32_16x16x32_bf16 v[14:17], v[148:151], v[204:207], v[14:17]
	v_mfma_f32_16x16x32_bf16 v[10:13], v[156:159], v[204:207], v[10:13]
	v_mfma_f32_16x16x32_bf16 v[54:57], v[160:163], v[176:179], v[54:57]
	v_mfma_f32_16x16x32_bf16 v[50:53], v[168:171], v[176:179], v[50:53]
	v_mfma_f32_16x16x32_bf16 v[38:41], v[160:163], v[184:187], v[38:41]
	v_mfma_f32_16x16x32_bf16 v[34:37], v[168:171], v[184:187], v[34:37]
	v_mfma_f32_16x16x32_bf16 v[22:25], v[160:163], v[192:195], v[22:25]
	v_mfma_f32_16x16x32_bf16 v[18:21], v[168:171], v[192:195], v[18:21]
	v_mfma_f32_16x16x32_bf16 v[6:9], v[160:163], v[200:203], v[6:9]
	v_mfma_f32_16x16x32_bf16 v[2:5], v[168:171], v[200:203], v[2:5]
	v_mfma_f32_16x16x32_bf16 v[54:57], v[164:167], v[180:183], v[54:57]
	v_mfma_f32_16x16x32_bf16 v[50:53], v[172:175], v[180:183], v[50:53]
	v_mfma_f32_16x16x32_bf16 v[38:41], v[164:167], v[188:191], v[38:41]
	v_mfma_f32_16x16x32_bf16 v[34:37], v[172:175], v[188:191], v[34:37]
	v_mfma_f32_16x16x32_bf16 v[22:25], v[164:167], v[196:199], v[22:25]
	v_mfma_f32_16x16x32_bf16 v[18:21], v[172:175], v[196:199], v[18:21]
	v_mfma_f32_16x16x32_bf16 v[6:9], v[164:167], v[204:207], v[6:9]
	v_mfma_f32_16x16x32_bf16 v[2:5], v[172:175], v[204:207], v[2:5]
	s_barrier
	s_setprio 0
	s_add_u32 s8, s8, 0x100
	s_addc_u32 s9, s9, 0
	s_add_u32 s12, s12, 0x100
	s_addc_u32 s13, s13, 0
	s_mov_b32 s10, s14

; #define PG8_STAGE(bufoff, gbase, voff) do { _Pragma("unroll") for (int _i = 0; _i < 2; ++_i) \
;         __builtin_amdgcn_global_load_lds((const unsigned*)((const char*)(gbase) + (voff)[_i]), (PG8_LAS unsigned*)(lds + (bufoff) + ldsw + _i * 8192), 16, 0, 0); } while (0)
; #define PG8_LDA(dst, b, h) do { _Pragma("unroll") for (int m = 0; m < 4; ++m) _Pragma("unroll") for (int k = 0; k < 2; ++k) dst[m][k] = *(const PG8_LAS bf16x8*)(lds + PG8_SA(b, h) + aoff + m * 2048 + k * 1024); } while (0)
; #define PG8_LDB(dst, b, h) do { _Pragma("unroll") for (int n = 0; n < 2; ++n) _Pragma("unroll") for (int k = 0; k < 2; ++k) dst[n][k] = *(const PG8_LAS bf16x8*)(lds + PG8_SB(b, h) + boff + n * 2048 + k * 1024); } while (0)
; #define PG8_WAIT_V(n) asm volatile("s_waitcnt vmcnt(" #n ")" ::: "memory")
; #define PG8_WAIT_L(n) asm volatile("s_waitcnt lgkmcnt(" #n ")" ::: "memory")
; #define PG8_BAR __builtin_amdgcn_s_barrier()
; #define PG8_SCHED __builtin_amdgcn_sched_barrier(0)
; template <class Epi, class Sched, bool ALIGN_EPI = false, bool SP2 = false>
; __device__ __forceinline__ void gemm_phase(PG8_LAS unsigned char* lds, const Gemm g, const Sched& S, const Epi& E) {
;     ...
;         const char* nA = has_next ? (const char*)g.A + (size_t)nxt.pm * tstep : cA; const char* nB = has_next ? (const char*)g.Bt + (size_t)nxt.pn * tstep : cB;
;         for (int t = 0; t < nt; t += 2) {
;             const bool last = (t == nt - 2);
;             const char* a1 = cA + (size_t)(t + 1) * kstep;
;             const char* a2 = last ? nA : cA + (size_t)(t + 2) * kstep; const char* b2 = last ? nB : cB + (size_t)(t + 2) * kstep;
;             const char* a3 = a2 + kstep; const char* b3 = b2 + kstep;
;             if (last && has_next) S.a_ready(nxt);
;             if constexpr (SP2) {
;             PG8_LDB(B0, 0, 0); PG8_LDB(B1, 0, 1); PG8_SCHED; PG8_LDA(At, 0, 0); PG8_STAGE(PG8_SA(1, 1), a1 + hstep, voffA);
;             PG8_WAIT_V(8); PG8_WAIT_L(0); PG8_BAR; PG8_MMA(0, 0, At, B0); PG8_MMA(0, 1, At, B1); PG8_BAR; PG8_SCHED;
;             PG8_LDA(At, 0, 1); PG8_STAGE(PG8_SB(0, 0), b2, voffB); PG8_STAGE(PG8_SB(0, 1), b2 + hstep, voffB); PG8_STAGE(PG8_SA(0, 0), a2, voffA);
;             PG8_WAIT_V(8); PG8_WAIT_L(0); PG8_BAR; PG8_MMA(1, 0, At, B0); PG8_MMA(1, 1, At, B1); PG8_BAR; PG8_SCHED;
.Lstg4_done:
	s_ashr_i32 s37, s36, 31
	s_lshl_b64 s[26:27], s[36:37], 20
	s_add_u32 s26, s18, s26
	s_addc_u32 s27, s19, s27
	s_and_b64 s[44:45], s[40:41], exec
	s_cselect_b32 s37, s27, s51
	s_cselect_b32 s43, s26, s50
	s_ashr_i32 s23, s22, 31
	s_lshl_b64 s[44:45], s[22:23], 20
	s_add_u32 s44, s96, s44
	s_addc_u32 s45, s97, s45
	s_and_b64 s[52:53], s[40:41], exec
	s_cselect_b32 s23, s45, s11
	s_cselect_b32 s56, s44, s10
	s_add_u32 s50, s50, 0x80080
	s_addc_u32 s51, s51, 0
	s_add_u32 s57, s10, 0x100
	s_addc_u32 s58, s11, 0
	s_mov_b32 s59, -2
	v_add_u32_e32 v248, 0x10000, v149
	s_add_u32 s10, s50, 0xfff80080
	s_addc_u32 s11, s51, -1
	s_add_i32 s60, 0, 0x10000
	s_cmp_eq_u32 s59, 28
	s_cselect_b32 s53, s37, s11
	s_cselect_b32 s52, s43, s10
	s_cselect_b32 s11, s23, s58
	s_cselect_b32 s10, s56, s57
	s_add_i32 s62, 0, 0x14000
	ds_read_b128 v[140:143], v248
	ds_read_b128 v[152:155], v248 offset:1024
	ds_read_b128 v[156:159], v248 offset:2048
	ds_read_b128 v[160:163], v248 offset:3072
	ds_read_b128 v[164:167], v248 offset:16384
	ds_read_b128 v[168:171], v248 offset:17408
	ds_read_b128 v[172:175], v248 offset:18432
	ds_read_b128 v[176:179], v248 offset:19456
	s_add_i32 m0, s5, 0xc000
	ds_read_b128 v[180:183], v151
	ds_read_b128 v[184:187], v151 offset:1024
	ds_read_b128 v[188:191], v151 offset:2048
	ds_read_b128 v[192:195], v151 offset:3072
	ds_read_b128 v[196:199], v151 offset:4096
	ds_read_b128 v[200:203], v151 offset:5120
	ds_read_b128 v[204:207], v151 offset:6144
	ds_read_b128 v[208:211], v151 offset:7168
	global_load_lds_dwordx4 v136, s[50:51]
	s_add_i32 m0, s5, 0xe000
	s_nop 0
	global_load_lds_dwordx4 v138, s[50:51]
	s_waitcnt lgkmcnt(0)
	s_setprio 1
	s_barrier
	v_mfma_f32_16x16x32_bf16 v[126:129], v[140:143], v[180:183], 0
	v_mfma_f32_16x16x32_bf16 v[122:125], v[156:159], v[180:183], 0
	v_mfma_f32_16x16x32_bf16 v[110:113], v[140:143], v[188:191], 0
	v_mfma_f32_16x16x32_bf16 v[106:109], v[156:159], v[188:191], 0
	v_mfma_f32_16x16x32_bf16 v[94:97], v[140:143], v[196:199], 0
	v_mfma_f32_16x16x32_bf16 v[90:93], v[156:159], v[196:199], 0
	v_mfma_f32_16x16x32_bf16 v[78:81], v[140:143], v[204:207], 0
	v_mfma_f32_16x16x32_bf16 v[74:77], v[156:159], v[204:207], 0
	v_mfma_f32_16x16x32_bf16 v[126:129], v[152:155], v[184:187], v[126:129]
	v_mfma_f32_16x16x32_bf16 v[122:125], v[160:163], v[184:187], v[122:125]
	v_mfma_f32_16x16x32_bf16 v[110:113], v[152:155], v[192:195], v[110:113]
	v_mfma_f32_16x16x32_bf16 v[106:109], v[160:163], v[192:195], v[106:109]
	v_mfma_f32_16x16x32_bf16 v[94:97], v[152:155], v[200:203], v[94:97]
	v_mfma_f32_16x16x32_bf16 v[90:93], v[160:163], v[200:203], v[90:93]
	v_mfma_f32_16x16x32_bf16 v[78:81], v[152:155], v[208:211], v[78:81]
	v_mfma_f32_16x16x32_bf16 v[74:77], v[160:163], v[208:211], v[74:77]
	v_mfma_f32_16x16x32_bf16 v[118:121], v[164:167], v[180:183], 0
	v_mfma_f32_16x16x32_bf16 v[114:117], v[172:175], v[180:183], 0
	v_mfma_f32_16x16x32_bf16 v[102:105], v[164:167], v[188:191], 0
	v_mfma_f32_16x16x32_bf16 v[98:101], v[172:175], v[188:191], 0
	v_mfma_f32_16x16x32_bf16 v[86:89], v[164:167], v[196:199], 0
	v_mfma_f32_16x16x32_bf16 v[82:85], v[172:175], v[196:199], 0
	v_mfma_f32_16x16x32_bf16 v[70:73], v[164:167], v[204:207], 0
	v_mfma_f32_16x16x32_bf16 v[66:69], v[172:175], v[204:207], 0
	v_mfma_f32_16x16x32_bf16 v[118:121], v[168:171], v[184:187], v[118:121]
	v_mfma_f32_16x16x32_bf16 v[114:117], v[176:179], v[184:187], v[114:117]
	v_mfma_f32_16x16x32_bf16 v[102:105], v[168:171], v[192:195], v[102:105]
	v_mfma_f32_16x16x32_bf16 v[98:101], v[176:179], v[192:195], v[98:101]
	v_mfma_f32_16x16x32_bf16 v[86:89], v[168:171], v[200:203], v[86:89]
	v_mfma_f32_16x16x32_bf16 v[82:85], v[176:179], v[200:203], v[82:85]
	v_mfma_f32_16x16x32_bf16 v[70:73], v[168:171], v[208:211], v[70:73]
	v_mfma_f32_16x16x32_bf16 v[66:69], v[176:179], v[208:211], v[66:69]
	s_barrier
	s_setprio 0
	s_add_i32 s60, s60, s4
	s_add_u32 s100, s10, 0x80
	s_addc_u32 s101, s11, 0
	s_mov_b32 m0, s60
	ds_read_b128 v[180:183], v151 offset:16384
	ds_read_b128 v[184:187], v151 offset:17408
	ds_read_b128 v[188:191], v151 offset:18432
	ds_read_b128 v[192:195], v151 offset:19456
	ds_read_b128 v[196:199], v151 offset:20480
	ds_read_b128 v[200:203], v151 offset:21504
	ds_read_b128 v[204:207], v151 offset:22528
	ds_read_b128 v[208:211], v151 offset:23552
	global_load_lds_dwordx4 v0, s[10:11]
	s_add_i32 m0, s60, 0x2000
	s_add_u32 s60, s10, 0x80000
	s_addc_u32 s61, s11, 0
	s_add_i32 s62, s62, s4
	global_load_lds_dwordx4 v134, s[10:11]
	s_mov_b32 m0, s62
	s_add_u32 s98, s52, 0x80
	s_addc_u32 s99, s53, 0
	global_load_lds_dwordx4 v0, s[60:61]
	s_add_i32 m0, s62, 0x2000
	s_nop 0
	global_load_lds_dwordx4 v134, s[60:61]
	s_mov_b32 m0, s5
	s_nop 0
	global_load_lds_dwordx4 v130, s[52:53]
	s_mov_b32 m0, s6
	s_nop 0
	global_load_lds_dwordx4 v132, s[52:53]
	s_waitcnt vmcnt(8) lgkmcnt(0)
	s_setprio 1
	s_barrier
; #define PG8_STAGE(bufoff, gbase, voff) do { _Pragma("unroll") for (int _i = 0; _i < 2; ++_i) \
;         __builtin_amdgcn_global_load_lds((const unsigned*)((const char*)(gbase) + (voff)[_i]), (PG8_LAS unsigned*)(lds + (bufoff) + ldsw + _i * 8192), 16, 0, 0); } while (0)
; #define PG8_LDA(dst, b, h) do { _Pragma("unroll") for (int m = 0; m < 4; ++m) _Pragma("unroll") for (int k = 0; k < 2; ++k) dst[m][k] = *(const PG8_LAS bf16x8*)(lds + PG8_SA(b, h) + aoff + m * 2048 + k * 1024); } while (0)
; #define PG8_LDB(dst, b, h) do { _Pragma("unroll") for (int n = 0; n < 2; ++n) _Pragma("unroll") for (int k = 0; k < 2; ++k) dst[n][k] = *(const PG8_LAS bf16x8*)(lds + PG8_SB(b, h) + boff + n * 2048 + k * 1024); } while (0)
; #define PG8_MMA(ai, bj, At, Bt) do { __builtin_amdgcn_s_setprio(1); _Pragma("unroll") for (int m = 0; m < 4; ++m) _Pragma("unroll") for (int n = 0; n < 2; ++n) _Pragma("unroll") for (int k = 0; k < 2; ++k) \
;         acc[ai][bj][m][n] = __builtin_amdgcn_mfma_f32_16x16x32_bf16(Bt[n][k], At[m][k], acc[ai][bj][m][n], 0, 0, 0); __builtin_amdgcn_s_setprio(0); } while (0)
; #define PG8_WAIT_V(n) asm volatile("s_waitcnt vmcnt(" #n ")" ::: "memory")
; #define PG8_WAIT_L(n) asm volatile("s_waitcnt lgkmcnt(" #n ")" ::: "memory")
; #define PG8_BAR __builtin_amdgcn_s_barrier()
; #define PG8_SCHED __builtin_amdgcn_sched_barrier(0)
; template <class Epi, class Sched, bool ALIGN_EPI = false, bool SP2 = false>
; __device__ __forceinline__ void gemm_phase(PG8_LAS unsigned char* lds, const Gemm g, const Sched& S, const Epi& E) {
;     ...
;             PG8_LDA(At, 0, 1); PG8_STAGE(PG8_SB(0, 0), b2, voffB); PG8_STAGE(PG8_SB(0, 1), b2 + hstep, voffB); PG8_STAGE(PG8_SA(0, 0), a2, voffA);
;             PG8_WAIT_V(8); PG8_WAIT_L(0); PG8_BAR; PG8_MMA(1, 0, At, B0); PG8_MMA(1, 1, At, B1); PG8_BAR; PG8_SCHED;
;             PG8_LDB(B0, 1, 0); PG8_LDB(B1, 1, 1); PG8_SCHED; PG8_LDA(At, 1, 0); PG8_STAGE(PG8_SA(0, 1), a2 + hstep, voffA);
;             PG8_WAIT_V(8); PG8_WAIT_L(0); PG8_BAR; PG8_MMA(0, 0, At, B0); PG8_MMA(0, 1, At, B1); PG8_BAR; PG8_SCHED;
	v_mfma_f32_16x16x32_bf16 v[62:65], v[140:143], v[180:183], 0
	v_mfma_f32_16x16x32_bf16 v[58:61], v[156:159], v[180:183], 0
	v_mfma_f32_16x16x32_bf16 v[46:49], v[140:143], v[188:191], 0
	v_mfma_f32_16x16x32_bf16 v[42:45], v[156:159], v[188:191], 0
	v_mfma_f32_16x16x32_bf16 v[30:33], v[140:143], v[196:199], 0
	v_mfma_f32_16x16x32_bf16 v[26:29], v[156:159], v[196:199], 0
	v_mfma_f32_16x16x32_bf16 v[14:17], v[140:143], v[204:207], 0
	v_mfma_f32_16x16x32_bf16 v[10:13], v[156:159], v[204:207], 0
	v_mfma_f32_16x16x32_bf16 v[62:65], v[152:155], v[184:187], v[62:65]
	v_mfma_f32_16x16x32_bf16 v[58:61], v[160:163], v[184:187], v[58:61]
	v_mfma_f32_16x16x32_bf16 v[46:49], v[152:155], v[192:195], v[46:49]
	v_mfma_f32_16x16x32_bf16 v[42:45], v[160:163], v[192:195], v[42:45]
	v_mfma_f32_16x16x32_bf16 v[30:33], v[152:155], v[200:203], v[30:33]
	v_mfma_f32_16x16x32_bf16 v[26:29], v[160:163], v[200:203], v[26:29]
	v_mfma_f32_16x16x32_bf16 v[14:17], v[152:155], v[208:211], v[14:17]
	v_mfma_f32_16x16x32_bf16 v[10:13], v[160:163], v[208:211], v[10:13]
	v_mfma_f32_16x16x32_bf16 v[54:57], v[164:167], v[180:183], 0
	v_mfma_f32_16x16x32_bf16 v[50:53], v[172:175], v[180:183], 0
	v_mfma_f32_16x16x32_bf16 v[38:41], v[164:167], v[188:191], 0
	v_mfma_f32_16x16x32_bf16 v[34:37], v[172:175], v[188:191], 0
	v_mfma_f32_16x16x32_bf16 v[22:25], v[164:167], v[196:199], 0
	v_mfma_f32_16x16x32_bf16 v[18:21], v[172:175], v[196:199], 0
	v_mfma_f32_16x16x32_bf16 v[6:9], v[164:167], v[204:207], 0
	v_mfma_f32_16x16x32_bf16 v[2:5], v[172:175], v[204:207], 0
	v_mfma_f32_16x16x32_bf16 v[54:57], v[168:171], v[184:187], v[54:57]
	v_mfma_f32_16x16x32_bf16 v[50:53], v[176:179], v[184:187], v[50:53]
	v_mfma_f32_16x16x32_bf16 v[38:41], v[168:171], v[192:195], v[38:41]
	v_mfma_f32_16x16x32_bf16 v[34:37], v[176:179], v[192:195], v[34:37]
	v_mfma_f32_16x16x32_bf16 v[22:25], v[168:171], v[200:203], v[22:25]
	v_mfma_f32_16x16x32_bf16 v[18:21], v[176:179], v[200:203], v[18:21]
	v_mfma_f32_16x16x32_bf16 v[6:9], v[168:171], v[208:211], v[6:9]
	v_mfma_f32_16x16x32_bf16 v[2:5], v[176:179], v[208:211], v[2:5]
	s_barrier
	s_setprio 0
	s_add_i32 s60, 0, 0x18000
	s_add_i32 s61, 0, 0x1c000
	ds_read_b128 v[140:143], v248 offset:32768
	ds_read_b128 v[152:155], v248 offset:33792
	ds_read_b128 v[156:159], v248 offset:34816
	ds_read_b128 v[160:163], v248 offset:35840
	ds_read_b128 v[164:167], v248 offset:49152
	ds_read_b128 v[168:171], v248 offset:50176
	ds_read_b128 v[172:175], v248 offset:51200
	ds_read_b128 v[176:179], v248 offset:52224
	s_add_u32 s52, s52, 0x80000
	s_addc_u32 s53, s53, 0
	s_mov_b32 m0, s7
	ds_read_b128 v[180:183], v151 offset:32768
	ds_read_b128 v[184:187], v151 offset:33792
	ds_read_b128 v[188:191], v151 offset:34816
	ds_read_b128 v[192:195], v151 offset:35840
	ds_read_b128 v[196:199], v151 offset:36864
	ds_read_b128 v[200:203], v151 offset:37888
	ds_read_b128 v[204:207], v151 offset:38912
	ds_read_b128 v[208:211], v151 offset:39936
	global_load_lds_dwordx4 v130, s[52:53]
	s_mov_b32 m0, s17
	s_nop 0
	global_load_lds_dwordx4 v132, s[52:53]
	s_waitcnt vmcnt(8) lgkmcnt(0)
	s_setprio 1
	s_barrier
	v_mfma_f32_16x16x32_bf16 v[126:129], v[140:143], v[180:183], v[126:129]
	v_mfma_f32_16x16x32_bf16 v[122:125], v[156:159], v[180:183], v[122:125]
	v_mfma_f32_16x16x32_bf16 v[110:113], v[140:143], v[188:191], v[110:113]
	v_mfma_f32_16x16x32_bf16 v[106:109], v[156:159], v[188:191], v[106:109]
	v_mfma_f32_16x16x32_bf16 v[94:97], v[140:143], v[196:199], v[94:97]
	v_mfma_f32_16x16x32_bf16 v[90:93], v[156:159], v[196:199], v[90:93]
	v_mfma_f32_16x16x32_bf16 v[78:81], v[140:143], v[204:207], v[78:81]
	v_mfma_f32_16x16x32_bf16 v[74:77], v[156:159], v[204:207], v[74:77]
	v_mfma_f32_16x16x32_bf16 v[126:129], v[152:155], v[184:187], v[126:129]
	v_mfma_f32_16x16x32_bf16 v[122:125], v[160:163], v[184:187], v[122:125]
	v_mfma_f32_16x16x32_bf16 v[110:113], v[152:155], v[192:195], v[110:113]
	v_mfma_f32_16x16x32_bf16 v[106:109], v[160:163], v[192:195], v[106:109]
	v_mfma_f32_16x16x32_bf16 v[94:97], v[152:155], v[200:203], v[94:97]
	v_mfma_f32_16x16x32_bf16 v[90:93], v[160:163], v[200:203], v[90:93]
	v_mfma_f32_16x16x32_bf16 v[78:81], v[152:155], v[208:211], v[78:81]
	v_mfma_f32_16x16x32_bf16 v[74:77], v[160:163], v[208:211], v[74:77]
	v_mfma_f32_16x16x32_bf16 v[118:121], v[164:167], v[180:183], v[118:121]
	v_mfma_f32_16x16x32_bf16 v[114:117], v[172:175], v[180:183], v[114:117]
	v_mfma_f32_16x16x32_bf16 v[102:105], v[164:167], v[188:191], v[102:105]
	v_mfma_f32_16x16x32_bf16 v[98:101], v[172:175], v[188:191], v[98:101]
	v_mfma_f32_16x16x32_bf16 v[86:89], v[164:167], v[196:199], v[86:89]
	v_mfma_f32_16x16x32_bf16 v[82:85], v[172:175], v[196:199], v[82:85]
	v_mfma_f32_16x16x32_bf16 v[70:73], v[164:167], v[204:207], v[70:73]
	v_mfma_f32_16x16x32_bf16 v[66:69], v[172:175], v[204:207], v[66:69]
	v_mfma_f32_16x16x32_bf16 v[118:121], v[168:171], v[184:187], v[118:121]
	v_mfma_f32_16x16x32_bf16 v[114:117], v[176:179], v[184:187], v[114:117]
	v_mfma_f32_16x16x32_bf16 v[102:105], v[168:171], v[192:195], v[102:105]
	v_mfma_f32_16x16x32_bf16 v[98:101], v[176:179], v[192:195], v[98:101]
	v_mfma_f32_16x16x32_bf16 v[86:89], v[168:171], v[200:203], v[86:89]
	v_mfma_f32_16x16x32_bf16 v[82:85], v[176:179], v[200:203], v[82:85]
	v_mfma_f32_16x16x32_bf16 v[70:73], v[168:171], v[208:211], v[70:73]
	v_mfma_f32_16x16x32_bf16 v[66:69], v[176:179], v[208:211], v[66:69]
	s_barrier
; #define PG8_STAGE(bufoff, gbase, voff) do { _Pragma("unroll") for (int _i = 0; _i < 2; ++_i) \
;         __builtin_amdgcn_global_load_lds((const unsigned*)((const char*)(gbase) + (voff)[_i]), (PG8_LAS unsigned*)(lds + (bufoff) + ldsw + _i * 8192), 16, 0, 0); } while (0)
; #define PG8_LDA(dst, b, h) do { _Pragma("unroll") for (int m = 0; m < 4; ++m) _Pragma("unroll") for (int k = 0; k < 2; ++k) dst[m][k] = *(const PG8_LAS bf16x8*)(lds + PG8_SA(b, h) + aoff + m * 2048 + k * 1024); } while (0)
; #define PG8_MMA(ai, bj, At, Bt) do { __builtin_amdgcn_s_setprio(1); _Pragma("unroll") for (int m = 0; m < 4; ++m) _Pragma("unroll") for (int n = 0; n < 2; ++n) _Pragma("unroll") for (int k = 0; k < 2; ++k) \
;         acc[ai][bj][m][n] = __builtin_amdgcn_mfma_f32_16x16x32_bf16(Bt[n][k], At[m][k], acc[ai][bj][m][n], 0, 0, 0); __builtin_amdgcn_s_setprio(0); } while (0)
; #define PG8_WAIT_V(n) asm volatile("s_waitcnt vmcnt(" #n ")" ::: "memory")
; #define PG8_WAIT_L(n) asm volatile("s_waitcnt lgkmcnt(" #n ")" ::: "memory")
; #define PG8_BAR __builtin_amdgcn_s_barrier()
; #define PG8_SCHED __builtin_amdgcn_sched_barrier(0)
; template <class Epi, class Sched, bool ALIGN_EPI = false, bool SP2 = false>
; __device__ __forceinline__ void gemm_phase(PG8_LAS unsigned char* lds, const Gemm g, const Sched& S, const Epi& E) {
;     ...
;             PG8_LDA(At, 1, 1); PG8_STAGE(PG8_SB(1, 0), b3, voffB); PG8_STAGE(PG8_SB(1, 1), b3 + hstep, voffB); PG8_STAGE(PG8_SA(1, 0), a3, voffA);
;             PG8_WAIT_V(8); PG8_WAIT_L(0); PG8_BAR; PG8_MMA(1, 0, At, B0); PG8_MMA(1, 1, At, B1); PG8_BAR; PG8_SCHED;
	s_setprio 0
	s_add_i32 s52, s60, s4
	s_mov_b32 m0, s52
	ds_read_b128 v[180:183], v151 offset:49152
	ds_read_b128 v[184:187], v151 offset:50176
	ds_read_b128 v[188:191], v151 offset:51200
	ds_read_b128 v[192:195], v151 offset:52224
	ds_read_b128 v[196:199], v151 offset:53248
	ds_read_b128 v[200:203], v151 offset:54272
	ds_read_b128 v[204:207], v151 offset:55296
	ds_read_b128 v[208:211], v151 offset:56320
	global_load_lds_dwordx4 v0, s[100:101]
	s_add_i32 m0, s52, 0x2000
	s_add_i32 s52, s61, s4
	global_load_lds_dwordx4 v134, s[100:101]
	s_add_u32 s10, s10, 0x80080
	s_addc_u32 s11, s11, 0
	s_mov_b32 m0, s52
	s_nop 0
	global_load_lds_dwordx4 v0, s[10:11]
	s_add_i32 m0, s52, 0x2000
	s_nop 0
	global_load_lds_dwordx4 v134, s[10:11]
	s_mov_b32 m0, s30
	s_nop 0
	global_load_lds_dwordx4 v130, s[98:99]
	s_mov_b32 m0, s47
	s_nop 0
	global_load_lds_dwordx4 v132, s[98:99]
	s_waitcnt vmcnt(8) lgkmcnt(0)
	s_setprio 1
	s_barrier
	v_mfma_f32_16x16x32_bf16 v[62:65], v[140:143], v[180:183], v[62:65]
	v_mfma_f32_16x16x32_bf16 v[58:61], v[156:159], v[180:183], v[58:61]
	v_mfma_f32_16x16x32_bf16 v[46:49], v[140:143], v[188:191], v[46:49]
	v_mfma_f32_16x16x32_bf16 v[42:45], v[156:159], v[188:191], v[42:45]
	v_mfma_f32_16x16x32_bf16 v[30:33], v[140:143], v[196:199], v[30:33]
	v_mfma_f32_16x16x32_bf16 v[26:29], v[156:159], v[196:199], v[26:29]
	v_mfma_f32_16x16x32_bf16 v[14:17], v[140:143], v[204:207], v[14:17]
	v_mfma_f32_16x16x32_bf16 v[10:13], v[156:159], v[204:207], v[10:13]
	v_mfma_f32_16x16x32_bf16 v[62:65], v[152:155], v[184:187], v[62:65]
	v_mfma_f32_16x16x32_bf16 v[58:61], v[160:163], v[184:187], v[58:61]
	v_mfma_f32_16x16x32_bf16 v[46:49], v[152:155], v[192:195], v[46:49]
	v_mfma_f32_16x16x32_bf16 v[42:45], v[160:163], v[192:195], v[42:45]
	v_mfma_f32_16x16x32_bf16 v[30:33], v[152:155], v[200:203], v[30:33]
	v_mfma_f32_16x16x32_bf16 v[26:29], v[160:163], v[200:203], v[26:29]
	v_mfma_f32_16x16x32_bf16 v[14:17], v[152:155], v[208:211], v[14:17]
	v_mfma_f32_16x16x32_bf16 v[10:13], v[160:163], v[208:211], v[10:13]
	v_mfma_f32_16x16x32_bf16 v[54:57], v[164:167], v[180:183], v[54:57]
	v_mfma_f32_16x16x32_bf16 v[50:53], v[172:175], v[180:183], v[50:53]
	v_mfma_f32_16x16x32_bf16 v[38:41], v[164:167], v[188:191], v[38:41]
	v_mfma_f32_16x16x32_bf16 v[34:37], v[172:175], v[188:191], v[34:37]
	v_mfma_f32_16x16x32_bf16 v[22:25], v[164:167], v[196:199], v[22:25]
	v_mfma_f32_16x16x32_bf16 v[18:21], v[172:175], v[196:199], v[18:21]
	v_mfma_f32_16x16x32_bf16 v[6:9], v[164:167], v[204:207], v[6:9]
	v_mfma_f32_16x16x32_bf16 v[2:5], v[172:175], v[204:207], v[2:5]
	v_mfma_f32_16x16x32_bf16 v[54:57], v[168:171], v[184:187], v[54:57]
	v_mfma_f32_16x16x32_bf16 v[50:53], v[176:179], v[184:187], v[50:53]
	v_mfma_f32_16x16x32_bf16 v[38:41], v[168:171], v[192:195], v[38:41]
	v_mfma_f32_16x16x32_bf16 v[34:37], v[176:179], v[192:195], v[34:37]
	v_mfma_f32_16x16x32_bf16 v[22:25], v[168:171], v[200:203], v[22:25]
	v_mfma_f32_16x16x32_bf16 v[18:21], v[176:179], v[200:203], v[18:21]
	v_mfma_f32_16x16x32_bf16 v[6:9], v[168:171], v[208:211], v[6:9]
	v_mfma_f32_16x16x32_bf16 v[2:5], v[176:179], v[208:211], v[2:5]
	s_barrier
	s_setprio 0
	s_add_i32 s59, s59, 2
	s_add_u32 s50, s50, 0x100
	s_addc_u32 s51, s51, 0
	s_add_u32 s57, s57, 0x100
	s_addc_u32 s58, s58, 0
